# S5 full pass: carry over previous chunks' end states rewritten by hand (all loads first, pointer increment, 6 VALU per step)
# speedup vs baseline: 1.0028x; 1.0028x over previous
.LBB0_435:
	s_lshl_b32 s0, s42, 4
	s_add_i32 s0, s0, s28
	s_lshl_b32 s0, s0, 9
	s_mov_b32 s1, 0
	s_mov_b32 s2, 0x2000
	s_mov_b32 s3, 0
	v_lshl_add_u64 v[54:55], v[66:67], 0, s[0:1]
	global_load_dwordx2 v[136:137], v[54:55], off
	v_lshl_add_u64 v[54:55], v[54:55], 0, s[2:3]
	global_load_dwordx2 v[138:139], v[54:55], off
	v_lshl_add_u64 v[54:55], v[54:55], 0, s[2:3]
	global_load_dwordx2 v[140:141], v[54:55], off
	v_lshl_add_u64 v[54:55], v[54:55], 0, s[2:3]
	global_load_dwordx2 v[142:143], v[54:55], off
	v_lshl_add_u64 v[54:55], v[54:55], 0, s[2:3]
	global_load_dwordx2 v[144:145], v[54:55], off
	v_lshl_add_u64 v[54:55], v[54:55], 0, s[2:3]
	global_load_dwordx2 v[146:147], v[54:55], off
	v_lshl_add_u64 v[54:55], v[54:55], 0, s[2:3]
	global_load_dwordx2 v[148:149], v[54:55], off
	v_lshl_add_u64 v[54:55], v[54:55], 0, s[2:3]
	global_load_dwordx2 v[150:151], v[54:55], off
	v_lshl_add_u64 v[54:55], v[54:55], 0, s[2:3]
	s_cmp_le_u32 s41, 8
	s_cbranch_scc1 .Lcarry_ld_done
	global_load_dwordx2 v[152:153], v[54:55], off
	v_lshl_add_u64 v[54:55], v[54:55], 0, s[2:3]
	global_load_dwordx2 v[154:155], v[54:55], off
	v_lshl_add_u64 v[54:55], v[54:55], 0, s[2:3]
	global_load_dwordx2 v[156:157], v[54:55], off
	v_lshl_add_u64 v[54:55], v[54:55], 0, s[2:3]
	global_load_dwordx2 v[158:159], v[54:55], off
	v_lshl_add_u64 v[54:55], v[54:55], 0, s[2:3]
	global_load_dwordx2 v[160:161], v[54:55], off
	v_lshl_add_u64 v[54:55], v[54:55], 0, s[2:3]
	global_load_dwordx2 v[162:163], v[54:55], off
	v_lshl_add_u64 v[54:55], v[54:55], 0, s[2:3]
	global_load_dwordx2 v[164:165], v[54:55], off
	v_lshl_add_u64 v[54:55], v[54:55], 0, s[2:3]
	global_load_dwordx2 v[166:167], v[54:55], off
	v_lshl_add_u64 v[54:55], v[54:55], 0, s[2:3]
	s_cmp_le_u32 s41, 16
	s_cbranch_scc1 .Lcarry_ld_done
	global_load_dwordx2 v[168:169], v[54:55], off
	v_lshl_add_u64 v[54:55], v[54:55], 0, s[2:3]
	global_load_dwordx2 v[170:171], v[54:55], off
	v_lshl_add_u64 v[54:55], v[54:55], 0, s[2:3]
	global_load_dwordx2 v[172:173], v[54:55], off
	v_lshl_add_u64 v[54:55], v[54:55], 0, s[2:3]
	global_load_dwordx2 v[174:175], v[54:55], off
	v_lshl_add_u64 v[54:55], v[54:55], 0, s[2:3]
	global_load_dwordx2 v[176:177], v[54:55], off
	v_lshl_add_u64 v[54:55], v[54:55], 0, s[2:3]
	global_load_dwordx2 v[178:179], v[54:55], off
	v_lshl_add_u64 v[54:55], v[54:55], 0, s[2:3]
	global_load_dwordx2 v[180:181], v[54:55], off
	v_lshl_add_u64 v[54:55], v[54:55], 0, s[2:3]
	global_load_dwordx2 v[182:183], v[54:55], off
	v_lshl_add_u64 v[54:55], v[54:55], 0, s[2:3]
	s_cmp_le_u32 s41, 24
	s_cbranch_scc1 .Lcarry_ld_done
	global_load_dwordx2 v[184:185], v[54:55], off
	v_lshl_add_u64 v[54:55], v[54:55], 0, s[2:3]
	global_load_dwordx2 v[186:187], v[54:55], off
	v_lshl_add_u64 v[54:55], v[54:55], 0, s[2:3]
	global_load_dwordx2 v[188:189], v[54:55], off
	v_lshl_add_u64 v[54:55], v[54:55], 0, s[2:3]
	global_load_dwordx2 v[190:191], v[54:55], off
	v_lshl_add_u64 v[54:55], v[54:55], 0, s[2:3]
	global_load_dwordx2 v[202:203], v[54:55], off
	v_lshl_add_u64 v[54:55], v[54:55], 0, s[2:3]
	global_load_dwordx2 v[204:205], v[54:55], off
	v_lshl_add_u64 v[54:55], v[54:55], 0, s[2:3]
	global_load_dwordx2 v[206:207], v[54:55], off
.Lcarry_ld_done:
	s_waitcnt vmcnt(0)
	v_mul_f32_e32 v52, v42, v93
	v_mul_f32_e32 v53, v42, v92
	v_fma_f32 v52, v41, v92, -v52
	v_fmac_f32_e32 v53, v41, v93
	v_add_f32_e32 v92, v136, v52
	v_add_f32_e32 v93, v137, v53
	s_cmp_le_u32 s41, 1
	s_cbranch_scc1 .Lcarry_done
	v_mul_f32_e32 v52, v42, v93
	v_mul_f32_e32 v53, v42, v92
	v_fma_f32 v52, v41, v92, -v52
	v_fmac_f32_e32 v53, v41, v93
	v_add_f32_e32 v92, v138, v52
	v_add_f32_e32 v93, v139, v53
	s_cmp_le_u32 s41, 2
	s_cbranch_scc1 .Lcarry_done
	v_mul_f32_e32 v52, v42, v93
	v_mul_f32_e32 v53, v42, v92
	v_fma_f32 v52, v41, v92, -v52
	v_fmac_f32_e32 v53, v41, v93
	v_add_f32_e32 v92, v140, v52
	v_add_f32_e32 v93, v141, v53
	s_cmp_le_u32 s41, 3
	s_cbranch_scc1 .Lcarry_done
	v_mul_f32_e32 v52, v42, v93
	v_mul_f32_e32 v53, v42, v92
	v_fma_f32 v52, v41, v92, -v52
	v_fmac_f32_e32 v53, v41, v93
	v_add_f32_e32 v92, v142, v52
	v_add_f32_e32 v93, v143, v53
	s_cmp_le_u32 s41, 4
	s_cbranch_scc1 .Lcarry_done
	v_mul_f32_e32 v52, v42, v93
	v_mul_f32_e32 v53, v42, v92
	v_fma_f32 v52, v41, v92, -v52
	v_fmac_f32_e32 v53, v41, v93
	v_add_f32_e32 v92, v144, v52
	v_add_f32_e32 v93, v145, v53
	s_cmp_le_u32 s41, 5
	s_cbranch_scc1 .Lcarry_done
	v_mul_f32_e32 v52, v42, v93
	v_mul_f32_e32 v53, v42, v92
	v_fma_f32 v52, v41, v92, -v52
	v_fmac_f32_e32 v53, v41, v93
	v_add_f32_e32 v92, v146, v52
	v_add_f32_e32 v93, v147, v53
	s_cmp_le_u32 s41, 6
	s_cbranch_scc1 .Lcarry_done
	v_mul_f32_e32 v52, v42, v93
	v_mul_f32_e32 v53, v42, v92
	v_fma_f32 v52, v41, v92, -v52
	v_fmac_f32_e32 v53, v41, v93
	v_add_f32_e32 v92, v148, v52
	v_add_f32_e32 v93, v149, v53
	s_cmp_le_u32 s41, 7
	s_cbranch_scc1 .Lcarry_done
	v_mul_f32_e32 v52, v42, v93
	v_mul_f32_e32 v53, v42, v92
	v_fma_f32 v52, v41, v92, -v52
	v_fmac_f32_e32 v53, v41, v93
	v_add_f32_e32 v92, v150, v52
	v_add_f32_e32 v93, v151, v53
	s_cmp_le_u32 s41, 8
	s_cbranch_scc1 .Lcarry_done
	v_mul_f32_e32 v52, v42, v93
	v_mul_f32_e32 v53, v42, v92
	v_fma_f32 v52, v41, v92, -v52
	v_fmac_f32_e32 v53, v41, v93
	v_add_f32_e32 v92, v152, v52
	v_add_f32_e32 v93, v153, v53
	s_cmp_le_u32 s41, 9
	s_cbranch_scc1 .Lcarry_done
	v_mul_f32_e32 v52, v42, v93
	v_mul_f32_e32 v53, v42, v92
	v_fma_f32 v52, v41, v92, -v52
	v_fmac_f32_e32 v53, v41, v93
	v_add_f32_e32 v92, v154, v52
	v_add_f32_e32 v93, v155, v53
	s_cmp_le_u32 s41, 10
	s_cbranch_scc1 .Lcarry_done
	v_mul_f32_e32 v52, v42, v93
	v_mul_f32_e32 v53, v42, v92
	v_fma_f32 v52, v41, v92, -v52
	v_fmac_f32_e32 v53, v41, v93
	v_add_f32_e32 v92, v156, v52
	v_add_f32_e32 v93, v157, v53
	s_cmp_le_u32 s41, 11
	s_cbranch_scc1 .Lcarry_done
	v_mul_f32_e32 v52, v42, v93
	v_mul_f32_e32 v53, v42, v92
	v_fma_f32 v52, v41, v92, -v52
	v_fmac_f32_e32 v53, v41, v93
	v_add_f32_e32 v92, v158, v52
	v_add_f32_e32 v93, v159, v53
	s_cmp_le_u32 s41, 12
	s_cbranch_scc1 .Lcarry_done
	v_mul_f32_e32 v52, v42, v93
	v_mul_f32_e32 v53, v42, v92
	v_fma_f32 v52, v41, v92, -v52
	v_fmac_f32_e32 v53, v41, v93
	v_add_f32_e32 v92, v160, v52
	v_add_f32_e32 v93, v161, v53
	s_cmp_le_u32 s41, 13
	s_cbranch_scc1 .Lcarry_done
	v_mul_f32_e32 v52, v42, v93
	v_mul_f32_e32 v53, v42, v92
	v_fma_f32 v52, v41, v92, -v52
	v_fmac_f32_e32 v53, v41, v93
	v_add_f32_e32 v92, v162, v52
	v_add_f32_e32 v93, v163, v53
	s_cmp_le_u32 s41, 14
	s_cbranch_scc1 .Lcarry_done
	v_mul_f32_e32 v52, v42, v93
	v_mul_f32_e32 v53, v42, v92
	v_fma_f32 v52, v41, v92, -v52
	v_fmac_f32_e32 v53, v41, v93
	v_add_f32_e32 v92, v164, v52
	v_add_f32_e32 v93, v165, v53
	s_cmp_le_u32 s41, 15
	s_cbranch_scc1 .Lcarry_done
	v_mul_f32_e32 v52, v42, v93
	v_mul_f32_e32 v53, v42, v92
	v_fma_f32 v52, v41, v92, -v52
	v_fmac_f32_e32 v53, v41, v93
	v_add_f32_e32 v92, v166, v52
	v_add_f32_e32 v93, v167, v53
	s_cmp_le_u32 s41, 16
	s_cbranch_scc1 .Lcarry_done
	v_mul_f32_e32 v52, v42, v93
	v_mul_f32_e32 v53, v42, v92
	v_fma_f32 v52, v41, v92, -v52
	v_fmac_f32_e32 v53, v41, v93
	v_add_f32_e32 v92, v168, v52
	v_add_f32_e32 v93, v169, v53
	s_cmp_le_u32 s41, 17
	s_cbranch_scc1 .Lcarry_done
	v_mul_f32_e32 v52, v42, v93
	v_mul_f32_e32 v53, v42, v92
	v_fma_f32 v52, v41, v92, -v52
	v_fmac_f32_e32 v53, v41, v93
	v_add_f32_e32 v92, v170, v52
	v_add_f32_e32 v93, v171, v53
	s_cmp_le_u32 s41, 18
	s_cbranch_scc1 .Lcarry_done
	v_mul_f32_e32 v52, v42, v93
	v_mul_f32_e32 v53, v42, v92
	v_fma_f32 v52, v41, v92, -v52
	v_fmac_f32_e32 v53, v41, v93
	v_add_f32_e32 v92, v172, v52
	v_add_f32_e32 v93, v173, v53
	s_cmp_le_u32 s41, 19
	s_cbranch_scc1 .Lcarry_done
	v_mul_f32_e32 v52, v42, v93
	v_mul_f32_e32 v53, v42, v92
	v_fma_f32 v52, v41, v92, -v52
	v_fmac_f32_e32 v53, v41, v93
	v_add_f32_e32 v92, v174, v52
	v_add_f32_e32 v93, v175, v53
	s_cmp_le_u32 s41, 20
	s_cbranch_scc1 .Lcarry_done
	v_mul_f32_e32 v52, v42, v93
	v_mul_f32_e32 v53, v42, v92
	v_fma_f32 v52, v41, v92, -v52
	v_fmac_f32_e32 v53, v41, v93
	v_add_f32_e32 v92, v176, v52
	v_add_f32_e32 v93, v177, v53
	s_cmp_le_u32 s41, 21
	s_cbranch_scc1 .Lcarry_done
	v_mul_f32_e32 v52, v42, v93
	v_mul_f32_e32 v53, v42, v92
	v_fma_f32 v52, v41, v92, -v52
	v_fmac_f32_e32 v53, v41, v93
	v_add_f32_e32 v92, v178, v52
	v_add_f32_e32 v93, v179, v53
	s_cmp_le_u32 s41, 22
	s_cbranch_scc1 .Lcarry_done
	v_mul_f32_e32 v52, v42, v93
	v_mul_f32_e32 v53, v42, v92
	v_fma_f32 v52, v41, v92, -v52
	v_fmac_f32_e32 v53, v41, v93
	v_add_f32_e32 v92, v180, v52
	v_add_f32_e32 v93, v181, v53
	s_cmp_le_u32 s41, 23
	s_cbranch_scc1 .Lcarry_done
	v_mul_f32_e32 v52, v42, v93
	v_mul_f32_e32 v53, v42, v92
	v_fma_f32 v52, v41, v92, -v52
	v_fmac_f32_e32 v53, v41, v93
	v_add_f32_e32 v92, v182, v52
	v_add_f32_e32 v93, v183, v53
	s_cmp_le_u32 s41, 24
	s_cbranch_scc1 .Lcarry_done
	v_mul_f32_e32 v52, v42, v93
	v_mul_f32_e32 v53, v42, v92
	v_fma_f32 v52, v41, v92, -v52
	v_fmac_f32_e32 v53, v41, v93
	v_add_f32_e32 v92, v184, v52
	v_add_f32_e32 v93, v185, v53
	s_cmp_le_u32 s41, 25
	s_cbranch_scc1 .Lcarry_done
	v_mul_f32_e32 v52, v42, v93
	v_mul_f32_e32 v53, v42, v92
	v_fma_f32 v52, v41, v92, -v52
	v_fmac_f32_e32 v53, v41, v93
	v_add_f32_e32 v92, v186, v52
	v_add_f32_e32 v93, v187, v53
	s_cmp_le_u32 s41, 26
	s_cbranch_scc1 .Lcarry_done
	v_mul_f32_e32 v52, v42, v93
	v_mul_f32_e32 v53, v42, v92
	v_fma_f32 v52, v41, v92, -v52
	v_fmac_f32_e32 v53, v41, v93
	v_add_f32_e32 v92, v188, v52
	v_add_f32_e32 v93, v189, v53
	s_cmp_le_u32 s41, 27
	s_cbranch_scc1 .Lcarry_done
	v_mul_f32_e32 v52, v42, v93
	v_mul_f32_e32 v53, v42, v92
	v_fma_f32 v52, v41, v92, -v52
	v_fmac_f32_e32 v53, v41, v93
	v_add_f32_e32 v92, v190, v52
	v_add_f32_e32 v93, v191, v53
	s_cmp_le_u32 s41, 28
	s_cbranch_scc1 .Lcarry_done
	v_mul_f32_e32 v52, v42, v93
	v_mul_f32_e32 v53, v42, v92
	v_fma_f32 v52, v41, v92, -v52
	v_fmac_f32_e32 v53, v41, v93
	v_add_f32_e32 v92, v202, v52
	v_add_f32_e32 v93, v203, v53
	s_cmp_le_u32 s41, 29
	s_cbranch_scc1 .Lcarry_done
	v_mul_f32_e32 v52, v42, v93
	v_mul_f32_e32 v53, v42, v92
	v_fma_f32 v52, v41, v92, -v52
	v_fmac_f32_e32 v53, v41, v93
	v_add_f32_e32 v92, v204, v52
	v_add_f32_e32 v93, v205, v53
	s_cmp_le_u32 s41, 30
	s_cbranch_scc1 .Lcarry_done
	v_mul_f32_e32 v52, v42, v93
	v_mul_f32_e32 v53, v42, v92
	v_fma_f32 v52, v41, v92, -v52
	v_fmac_f32_e32 v53, v41, v93
	v_add_f32_e32 v92, v206, v52
	v_add_f32_e32 v93, v207, v53
.Lcarry_done:
	s_branch .LBB0_437
.LBB0_436:
	v_mov_b32_e32 v92, 0
	v_mov_b32_e32 v93, v92
